# adds: EpiRes second-half residual prefetch for the third residual GEMM instance (1024-deep GLA output projection)
# baseline (speedup 1.0000x reference)
; #define LAS __attribute__((address_space(3)))
; __device__ __forceinline__ unsigned pk2(float lo, float hi) { f32x2 v = {lo, hi}; bf16x2_t b = __builtin_convertvector(v, bf16x2_t); return __builtin_bit_cast(unsigned, b); }
; __device__ __forceinline__ float bflo(unsigned w) { return __uint_as_float(w << 16); }
; __device__ __forceinline__ float bfhi(unsigned w) { return __uint_as_float(w & 0xffff0000u); }
;     __device__ __forceinline__ void operator()(const f32x4 (&acc)[2][2][4][2], const Unit& u, int wr, int wc, int fr, int fq, LAS unsigned char* lds, int tid, State& st) const {
;         const int col0 = u.pn * BM + wc * 32 + 8 * fq;
;         LAS float* RED = (LAS float*)(lds + STAGE_BYTES);
; #pragma unroll
;         for (int ai = 0; ai < 2; ++ai) {
;             u32x4 bw[4][2];
; #pragma unroll
;             for (int m = 0; m < 4; ++m)
; #pragma unroll
;                 for (int bj = 0; bj < 2; ++bj) bw[m][bj] = *(const u32x4*)(xin + (size_t)(u.pm * BM + ai * HALF + wr * 64 + m * 16 + fr) * DM + col0 + bj * HALF);
; #pragma unroll
;             for (int m = 0; m < 4; ++m) {
;                 const int rl = ai * HALF + wr * 64 + m * 16 + fr;
;                 bf16_t* xp = xb + (size_t)(u.pm * BM + rl) * DM + col0;
;                 float sq = 0.f;
; #pragma unroll
;                 for (int bj = 0; bj < 2; ++bj) {
;                     const u32x4 w0 = bw[m][bj];
;                     const f32x4 o0 = (f32x4){bflo(w0.x), bfhi(w0.x), bflo(w0.y), bfhi(w0.y)} + acc[ai][bj][m][0];
;                     const f32x4 o1 = (f32x4){bflo(w0.z), bfhi(w0.z), bflo(w0.w), bfhi(w0.w)} + acc[ai][bj][m][1];
;                     sq += ((o0[0] * o0[0] + o0[1] * o0[1]) + (o0[2] * o0[2] + o0[3] * o0[3])) + ((o1[0] * o1[0] + o1[1] * o1[1]) + (o1[2] * o1[2] + o1[3] * o1[3]));
;                     u32x4 w; w.x = pk2(o0[0], o0[1]); w.y = pk2(o0[2], o0[3]); w.z = pk2(o1[0], o1[1]); w.w = pk2(o1[2], o1[3]);
;                     *(u32x4*)(xp + bj * HALF) = w;
;                 }
;                 sq += __shfl_xor(sq, 16); sq += __shfl_xor(sq, 32);
;                 if (fq == 0) RED[wc * 256 + rl] = sq;
.LBB0_361:
	v_and_b32_e32 v129, 64, v194
	v_xor_b32_e32 v128, 16, v194
	v_add_u32_e32 v129, 64, v129
	v_cmp_lt_i32_e32 vcc, v128, v129
	v_lshl_or_b32 v168, s12, 8, v188
	s_lshl_b32 s9, s50, 8
	v_cndmask_b32_e32 v128, v194, v128, vcc
	v_add_u32_e32 v170, s9, v177
	v_ashrrev_i32_e32 v169, 31, v168
	v_lshlrev_b32_e32 v198, 2, v128
	v_xor_b32_e32 v128, 32, v194
	v_cmp_lt_i32_e32 vcc, v128, v129
	v_lshlrev_b64 v[174:175], 1, v[168:169]
	v_ashrrev_i32_e32 v171, 31, v170
	v_cndmask_b32_e32 v128, v194, v128, vcc
	v_lshl_add_u64 v[172:173], s[84:85], 0, v[174:175]
	v_lshlrev_b64 v[204:205], 11, v[170:171]
	v_lshlrev_b32_e32 v197, 2, v128
	v_lshl_add_u64 v[128:129], v[172:173], 0, v[204:205]
	global_load_dwordx4 v[200:203], v[128:129], off
	global_load_dwordx4 v[152:155], v[128:129], off offset:256
	v_or_b32_e32 v128, 16, v170
	v_ashrrev_i32_e32 v129, 31, v128
	v_lshlrev_b64 v[128:129], 11, v[128:129]
	v_lshl_add_u64 v[128:129], v[172:173], 0, v[128:129]
	global_load_dwordx4 v[148:151], v[128:129], off
	global_load_dwordx4 v[144:147], v[128:129], off offset:256
	v_or_b32_e32 v128, 32, v170
	v_ashrrev_i32_e32 v129, 31, v128
	v_lshlrev_b64 v[128:129], 11, v[128:129]
	v_lshl_add_u64 v[128:129], v[172:173], 0, v[128:129]
	global_load_dwordx4 v[140:143], v[128:129], off
	global_load_dwordx4 v[136:139], v[128:129], off offset:256
	v_or_b32_e32 v128, 48, v170
	v_ashrrev_i32_e32 v129, 31, v128
	v_lshlrev_b64 v[128:129], 11, v[128:129]
	v_lshl_add_u64 v[128:129], v[172:173], 0, v[128:129]
	global_load_dwordx4 v[132:135], v[128:129], off
	s_nop 0
	global_load_dwordx4 v[128:131], v[128:129], off offset:256
	v_lshl_add_u64 v[204:205], s[84:85], 0, v[204:205]
	v_lshl_add_u64 v[174:175], v[204:205], 0, v[174:175]
	v_add_u32_e32 v234, 0x80, v170
	v_ashrrev_i32_e32 v235, 31, v234
	v_lshlrev_b64 v[234:235], 11, v[234:235]
	v_lshl_add_u64 v[234:235], v[172:173], 0, v[234:235]
	global_load_dwordx4 v[206:209], v[234:235], off
	global_load_dwordx4 v[210:213], v[234:235], off offset:256
	v_add_u32_e32 v234, 0x90, v170
	v_ashrrev_i32_e32 v235, 31, v234
	v_lshlrev_b64 v[234:235], 11, v[234:235]
	v_lshl_add_u64 v[234:235], v[172:173], 0, v[234:235]
	global_load_dwordx4 v[214:217], v[234:235], off
	global_load_dwordx4 v[218:221], v[234:235], off offset:256
	v_add_u32_e32 v234, 0xa0, v170
	v_ashrrev_i32_e32 v235, 31, v234
	v_lshlrev_b64 v[234:235], 11, v[234:235]
	v_lshl_add_u64 v[234:235], v[172:173], 0, v[234:235]
	global_load_dwordx4 v[222:225], v[234:235], off
	global_load_dwordx4 v[226:229], v[234:235], off offset:256
	v_add_u32_e32 v234, 0xb0, v170
	v_ashrrev_i32_e32 v235, 31, v234
	v_lshlrev_b64 v[234:235], 11, v[234:235]
	v_lshl_add_u64 v[234:235], v[172:173], 0, v[234:235]
	global_load_dwordx4 v[230:233], v[234:235], off
	s_waitcnt vmcnt(7)
	v_lshlrev_b32_e32 v204, 16, v200
	v_and_b32_e32 v205, 0xffff0000, v200
	v_lshlrev_b32_e32 v200, 16, v201
	v_and_b32_e32 v201, 0xffff0000, v201
	v_pk_add_f32 v[126:127], v[126:127], v[200:201]
	v_pk_add_f32 v[124:125], v[124:125], v[204:205]
	v_lshlrev_b32_e32 v200, 16, v202
	v_and_b32_e32 v201, 0xffff0000, v202
	v_lshlrev_b32_e32 v202, 16, v203
	v_and_b32_e32 v203, 0xffff0000, v203
	v_pk_add_f32 v[202:203], v[122:123], v[202:203]
	v_pk_add_f32 v[122:123], v[120:121], v[200:201]
	v_mul_f32_e32 v120, v125, v125
	v_mul_f32_e32 v121, v127, v127
	v_fmac_f32_e32 v120, v124, v124
	v_fmac_f32_e32 v121, v126, v126
	v_add_f32_e32 v120, v120, v121
	v_mul_f32_e32 v121, v123, v123
	v_mul_f32_e32 v171, v203, v203
	v_fmac_f32_e32 v121, v122, v122
	v_fmac_f32_e32 v171, v202, v202
	v_add_f32_e32 v121, v121, v171
	v_add_f32_e32 v171, v120, v121
	v_cvt_pk_bf16_f32 v120, v124, v125
	v_cvt_pk_bf16_f32 v121, v126, v127
	v_cvt_pk_bf16_f32 v122, v122, v123
	v_cvt_pk_bf16_f32 v123, v202, v203
	global_load_dwordx4 v[200:203], v[234:235], off offset:256
	global_store_dwordx4 v[174:175], v[120:123], off
	s_nop 1
	v_lshlrev_b32_e32 v120, 16, v152
	v_and_b32_e32 v121, 0xffff0000, v152
	v_lshlrev_b32_e32 v122, 16, v153
	v_and_b32_e32 v123, 0xffff0000, v153
	v_pk_add_f32 v[118:119], v[118:119], v[122:123]
	v_pk_add_f32 v[116:117], v[116:117], v[120:121]
	v_lshlrev_b32_e32 v120, 16, v154
	v_and_b32_e32 v121, 0xffff0000, v154
	v_lshlrev_b32_e32 v122, 16, v155
	v_and_b32_e32 v123, 0xffff0000, v155
	v_pk_add_f32 v[122:123], v[114:115], v[122:123]
	v_pk_add_f32 v[114:115], v[112:113], v[120:121]
	v_mul_f32_e32 v112, v117, v117
	v_mul_f32_e32 v113, v119, v119
	v_fmac_f32_e32 v112, v116, v116
	v_fmac_f32_e32 v113, v118, v118
	v_add_f32_e32 v112, v112, v113
	v_mul_f32_e32 v113, v115, v115
	v_mul_f32_e32 v120, v123, v123
	v_fmac_f32_e32 v113, v114, v114
	v_fmac_f32_e32 v120, v122, v122
	v_add_f32_e32 v113, v113, v120
	v_add_f32_e32 v112, v112, v113
	v_add_f32_e32 v120, v171, v112
	v_cvt_pk_bf16_f32 v112, v116, v117
	v_cvt_pk_bf16_f32 v113, v118, v119
	v_cvt_pk_bf16_f32 v114, v114, v115
	v_cvt_pk_bf16_f32 v115, v122, v123
	global_store_dwordx4 v[174:175], v[112:115], off offset:256
	ds_bpermute_b32 v112, v198, v120
	s_waitcnt lgkmcnt(0)
	v_add_f32_e32 v112, v120, v112
	ds_bpermute_b32 v113, v197, v112
	s_and_saveexec_b64 s[6:7], s[38:39]
	s_cbranch_execz .LBB0_363
	s_waitcnt lgkmcnt(0)
	v_add_f32_e32 v112, v112, v113
	ds_write_b32 v190, v112

; __device__ __forceinline__ unsigned pk2(float lo, float hi) { f32x2 v = {lo, hi}; bf16x2_t b = __builtin_convertvector(v, bf16x2_t); return __builtin_bit_cast(unsigned, b); }
; __device__ __forceinline__ float bflo(unsigned w) { return __uint_as_float(w << 16); }
; __device__ __forceinline__ float bfhi(unsigned w) { return __uint_as_float(w & 0xffff0000u); }
;     __device__ __forceinline__ void operator()(const f32x4 (&acc)[2][2][4][2], const Unit& u, int wr, int wc, int fr, int fq, LAS unsigned char* lds, int tid, State& st) const {
;     ...
;         for (int ai = 0; ai < 2; ++ai) {
;             u32x4 bw[4][2];
; #pragma unroll
;             for (int m = 0; m < 4; ++m)
; #pragma unroll
;                 for (int bj = 0; bj < 2; ++bj) bw[m][bj] = *(const u32x4*)(xin + (size_t)(u.pm * BM + ai * HALF + wr * 64 + m * 16 + fr) * DM + col0 + bj * HALF);
; #pragma unroll
;             for (int m = 0; m < 4; ++m) {
;                 const int rl = ai * HALF + wr * 64 + m * 16 + fr;
;                 bf16_t* xp = xb + (size_t)(u.pm * BM + rl) * DM + col0;
;                 float sq = 0.f;
; #pragma unroll
;                 for (int bj = 0; bj < 2; ++bj) {
;                     const u32x4 w0 = bw[m][bj];
;                     const f32x4 o0 = (f32x4){bflo(w0.x), bfhi(w0.x), bflo(w0.y), bfhi(w0.y)} + acc[ai][bj][m][0];
;                     const f32x4 o1 = (f32x4){bflo(w0.z), bfhi(w0.z), bflo(w0.w), bfhi(w0.w)} + acc[ai][bj][m][1];
;                     sq += ((o0[0] * o0[0] + o0[1] * o0[1]) + (o0[2] * o0[2] + o0[3] * o0[3])) + ((o1[0] * o1[0] + o1[1] * o1[1]) + (o1[2] * o1[2] + o1[3] * o1[3]));
;                     u32x4 w; w.x = pk2(o0[0], o0[1]); w.y = pk2(o0[2], o0[3]); w.z = pk2(o1[0], o1[1]); w.w = pk2(o1[2], o1[3]);
;                     *(u32x4*)(xp + bj * HALF) = w;
;                 }
;                 sq += __shfl_xor(sq, 16); sq += __shfl_xor(sq, 32);
;                 if (fq == 0) RED[wc * 256 + rl] = sq;
.LBB0_367:
	s_or_b64 exec, exec, s[6:7]
	v_lshlrev_b32_e32 v82, 16, v132
	v_and_b32_e32 v83, 0xffff0000, v132
	v_lshlrev_b32_e32 v84, 16, v133
	v_and_b32_e32 v85, 0xffff0000, v133
	v_pk_add_f32 v[78:79], v[78:79], v[84:85]
	v_pk_add_f32 v[76:77], v[76:77], v[82:83]
	v_lshlrev_b32_e32 v82, 16, v134
	v_and_b32_e32 v83, 0xffff0000, v134
	v_lshlrev_b32_e32 v84, 16, v135
	v_and_b32_e32 v85, 0xffff0000, v135
	v_pk_add_f32 v[84:85], v[74:75], v[84:85]
	v_pk_add_f32 v[74:75], v[72:73], v[82:83]
	v_mul_f32_e32 v72, v77, v77
	v_mul_f32_e32 v73, v79, v79
	v_fmac_f32_e32 v72, v76, v76
	v_fmac_f32_e32 v73, v78, v78
	v_add_f32_e32 v72, v72, v73
	v_mul_f32_e32 v73, v75, v75
	v_mul_f32_e32 v82, v85, v85
	v_fmac_f32_e32 v73, v74, v74
	v_fmac_f32_e32 v82, v84, v84
	v_add_f32_e32 v73, v73, v82
	v_add_f32_e32 v82, v72, v73
	v_cvt_pk_bf16_f32 v72, v76, v77
	v_cvt_pk_bf16_f32 v73, v78, v79
	v_lshlrev_b32_e32 v76, 16, v128
	v_and_b32_e32 v77, 0xffff0000, v128
	v_lshlrev_b32_e32 v78, 16, v129
	v_and_b32_e32 v79, 0xffff0000, v129
	v_pk_add_f32 v[70:71], v[70:71], v[78:79]
	v_pk_add_f32 v[68:69], v[68:69], v[76:77]
	v_lshlrev_b32_e32 v76, 16, v130
	v_and_b32_e32 v77, 0xffff0000, v130
	v_lshlrev_b32_e32 v78, 16, v131
	v_and_b32_e32 v79, 0xffff0000, v131
	v_pk_add_f32 v[76:77], v[64:65], v[76:77]
	v_mul_f32_e32 v64, v69, v69
	v_mul_f32_e32 v65, v71, v71
	v_pk_add_f32 v[78:79], v[66:67], v[78:79]
	v_fmac_f32_e32 v64, v68, v68
	v_fmac_f32_e32 v65, v70, v70
	v_add_f32_e32 v64, v64, v65
	v_mul_f32_e32 v65, v77, v77
	v_mul_f32_e32 v66, v79, v79
	v_fmac_f32_e32 v65, v76, v76
	v_fmac_f32_e32 v66, v78, v78
	v_add_f32_e32 v65, v65, v66
	v_add_f32_e32 v64, v64, v65
	v_add_f32_e32 v64, v82, v64
	ds_bpermute_b32 v65, v198, v64
	v_add_u32_e32 v80, s9, v193
	s_waitcnt lgkmcnt(1)
	v_ashrrev_i32_e32 v81, 31, v80
	v_lshlrev_b64 v[80:81], 11, v[80:81]
	v_lshl_add_u64 v[80:81], s[84:85], 0, v[80:81]
	s_waitcnt lgkmcnt(0)
	v_add_f32_e32 v64, v64, v65
	ds_bpermute_b32 v65, v197, v64
	v_lshl_add_u64 v[80:81], v[168:169], 1, v[80:81]
	v_cvt_pk_bf16_f32 v74, v74, v75
	v_cvt_pk_bf16_f32 v75, v84, v85
	v_cvt_pk_bf16_f32 v66, v68, v69
	v_cvt_pk_bf16_f32 v67, v70, v71
	v_cvt_pk_bf16_f32 v68, v76, v77
	v_cvt_pk_bf16_f32 v69, v78, v79
	global_store_dwordx4 v[80:81], v[72:75], off
	global_store_dwordx4 v[80:81], v[66:69], off offset:256
	s_and_saveexec_b64 s[6:7], s[38:39]
	s_cbranch_execz .LBB0_369
	s_waitcnt lgkmcnt(0)
	v_add_f32_e32 v64, v64, v65
	ds_write_b32 v190, v64 offset:192
.LBB0_369:
	s_or_b64 exec, exec, s[6:7]
	v_add_u32_e32 v64, 0x80, v170
	s_waitcnt lgkmcnt(0)
	v_ashrrev_i32_e32 v65, 31, v64
	v_lshlrev_b64 v[98:99], 11, v[64:65]
	v_lshl_add_u64 v[64:65], v[172:173], 0, v[98:99]
	s_waitcnt vmcnt(8)
	v_mov_b32_e32 v100, v206
	v_mov_b32_e32 v101, v207
	v_mov_b32_e32 v102, v208
	v_mov_b32_e32 v103, v209
	v_mov_b32_e32 v88, v210
	v_mov_b32_e32 v89, v211
	v_mov_b32_e32 v90, v212
	v_mov_b32_e32 v91, v213
	v_add_u32_e32 v64, 0x90, v170
	v_ashrrev_i32_e32 v65, 31, v64
	v_lshlrev_b64 v[96:97], 11, v[64:65]
	v_lshl_add_u64 v[64:65], v[172:173], 0, v[96:97]
	v_mov_b32_e32 v84, v214
	v_mov_b32_e32 v85, v215
	v_mov_b32_e32 v86, v216
	v_mov_b32_e32 v87, v217
	v_mov_b32_e32 v80, v218
	v_mov_b32_e32 v81, v219
	v_mov_b32_e32 v82, v220
	v_mov_b32_e32 v83, v221
	v_add_u32_e32 v64, 0xa0, v170
	v_ashrrev_i32_e32 v65, 31, v64
	v_lshlrev_b64 v[94:95], 11, v[64:65]
	v_lshl_add_u64 v[64:65], v[172:173], 0, v[94:95]
	v_mov_b32_e32 v76, v222
	v_mov_b32_e32 v77, v223
	v_mov_b32_e32 v78, v224
	v_mov_b32_e32 v79, v225
	v_mov_b32_e32 v72, v226
	v_mov_b32_e32 v73, v227
	v_mov_b32_e32 v74, v228
	v_mov_b32_e32 v75, v229
	v_add_u32_e32 v64, 0xb0, v170
	v_ashrrev_i32_e32 v65, 31, v64
	v_lshlrev_b64 v[92:93], 11, v[64:65]
	v_lshl_add_u64 v[64:65], v[172:173], 0, v[92:93]
	v_mov_b32_e32 v68, v230
	v_mov_b32_e32 v69, v231
	v_mov_b32_e32 v70, v232
	v_mov_b32_e32 v71, v233
	s_nop 0
	v_mov_b32_e32 v64, v200
	v_mov_b32_e32 v65, v201
	v_mov_b32_e32 v66, v202
	v_mov_b32_e32 v67, v203
	v_lshl_add_u64 v[98:99], s[84:85], 0, v[98:99]
	v_lshl_add_u64 v[98:99], v[168:169], 1, v[98:99]
	s_nop 0
	v_lshlrev_b32_e32 v104, 16, v100
	v_and_b32_e32 v105, 0xffff0000, v100
	v_lshlrev_b32_e32 v100, 16, v101
	v_and_b32_e32 v101, 0xffff0000, v101
	v_pk_add_f32 v[62:63], v[62:63], v[100:101]
	v_pk_add_f32 v[60:61], v[60:61], v[104:105]
	v_lshlrev_b32_e32 v100, 16, v102
	v_and_b32_e32 v101, 0xffff0000, v102
	v_lshlrev_b32_e32 v102, 16, v103
	v_and_b32_e32 v103, 0xffff0000, v103
	v_pk_add_f32 v[102:103], v[58:59], v[102:103]
	v_pk_add_f32 v[58:59], v[56:57], v[100:101]
	v_mul_f32_e32 v56, v61, v61
	v_mul_f32_e32 v57, v63, v63
	v_fmac_f32_e32 v56, v60, v60
	v_fmac_f32_e32 v57, v62, v62
	v_add_f32_e32 v56, v56, v57
	v_mul_f32_e32 v57, v59, v59
	v_mul_f32_e32 v100, v103, v103
	v_fmac_f32_e32 v57, v58, v58
	v_fmac_f32_e32 v100, v102, v102
	v_add_f32_e32 v57, v57, v100
	v_add_f32_e32 v100, v56, v57
	v_cvt_pk_bf16_f32 v56, v60, v61
	v_cvt_pk_bf16_f32 v57, v62, v63
	v_cvt_pk_bf16_f32 v58, v58, v59
	v_cvt_pk_bf16_f32 v59, v102, v103
	global_store_dwordx4 v[98:99], v[56:59], off
	s_nop 0
	s_nop 0
	v_lshlrev_b32_e32 v56, 16, v88
	v_and_b32_e32 v57, 0xffff0000, v88
	v_lshlrev_b32_e32 v58, 16, v89
	v_and_b32_e32 v59, 0xffff0000, v89
	v_pk_add_f32 v[54:55], v[54:55], v[58:59]
	v_pk_add_f32 v[52:53], v[52:53], v[56:57]
	v_lshlrev_b32_e32 v56, 16, v90
	v_and_b32_e32 v57, 0xffff0000, v90
	v_lshlrev_b32_e32 v58, 16, v91
	v_and_b32_e32 v59, 0xffff0000, v91
	v_pk_add_f32 v[58:59], v[50:51], v[58:59]
	v_pk_add_f32 v[50:51], v[48:49], v[56:57]
	v_mul_f32_e32 v48, v53, v53
	v_mul_f32_e32 v49, v55, v55
	v_fmac_f32_e32 v48, v52, v52
	v_fmac_f32_e32 v49, v54, v54
	v_add_f32_e32 v48, v48, v49
	v_mul_f32_e32 v49, v51, v51
	v_mul_f32_e32 v56, v59, v59
	v_fmac_f32_e32 v49, v50, v50
	v_fmac_f32_e32 v56, v58, v58
	v_add_f32_e32 v49, v49, v56
	v_add_f32_e32 v48, v48, v49
	v_add_f32_e32 v56, v100, v48
	v_cvt_pk_bf16_f32 v48, v52, v53
	v_cvt_pk_bf16_f32 v49, v54, v55
	v_cvt_pk_bf16_f32 v50, v50, v51
	v_cvt_pk_bf16_f32 v51, v58, v59
	global_store_dwordx4 v[98:99], v[48:51], off offset:256
	ds_bpermute_b32 v48, v198, v56
	s_waitcnt lgkmcnt(0)
	v_add_f32_e32 v48, v56, v48
	ds_bpermute_b32 v49, v197, v48
	s_and_saveexec_b64 s[6:7], s[38:39]
	s_cbranch_execz .LBB0_371
	s_waitcnt lgkmcnt(0)
	v_add_f32_e32 v48, v48, v49
	ds_write_b32 v190, v48 offset:512

; __device__ __forceinline__ unsigned pk2(float lo, float hi) { f32x2 v = {lo, hi}; bf16x2_t b = __builtin_convertvector(v, bf16x2_t); return __builtin_bit_cast(unsigned, b); }
; __device__ __forceinline__ float bflo(unsigned w) { return __uint_as_float(w << 16); }
; __device__ __forceinline__ float bfhi(unsigned w) { return __uint_as_float(w & 0xffff0000u); }
;     __device__ __forceinline__ void operator()(const f32x4 (&acc)[2][2][4][2], const Unit& u, int wr, int wc, int fr, int fq, LAS unsigned char* lds, int tid, State& st) const {
;     ...
;             for (int m = 0; m < 4; ++m) {
;                 const int rl = ai * HALF + wr * 64 + m * 16 + fr;
;                 bf16_t* xp = xb + (size_t)(u.pm * BM + rl) * DM + col0;
;                 float sq = 0.f;
; #pragma unroll
;                 for (int bj = 0; bj < 2; ++bj) {
;                     const u32x4 w0 = bw[m][bj];
;                     const f32x4 o0 = (f32x4){bflo(w0.x), bfhi(w0.x), bflo(w0.y), bfhi(w0.y)} + acc[ai][bj][m][0];
;                     const f32x4 o1 = (f32x4){bflo(w0.z), bfhi(w0.z), bflo(w0.w), bfhi(w0.w)} + acc[ai][bj][m][1];
;                     sq += ((o0[0] * o0[0] + o0[1] * o0[1]) + (o0[2] * o0[2] + o0[3] * o0[3])) + ((o1[0] * o1[0] + o1[1] * o1[1]) + (o1[2] * o1[2] + o1[3] * o1[3]));
;                     u32x4 w; w.x = pk2(o0[0], o0[1]); w.y = pk2(o0[2], o0[3]); w.z = pk2(o1[0], o1[1]); w.w = pk2(o1[2], o1[3]);
;                     *(u32x4*)(xp + bj * HALF) = w;
;                 }
;                 sq += __shfl_xor(sq, 16); sq += __shfl_xor(sq, 32);
;                 if (fq == 0) RED[wc * 256 + rl] = sq;
;             }
;         }
;         asm volatile("s_waitcnt lgkmcnt(0)" ::: "memory"); __builtin_amdgcn_s_barrier(); asm volatile("" ::: "memory");
;         if (tid < 256) ssq[(size_t)(u.pm * BM + tid) * 4 + u.pn] = (RED[tid] + RED[256 + tid]) + (RED[512 + tid] + RED[768 + tid]);
.LBB0_375:
	s_or_b64 exec, exec, s[6:7]
	s_nop 0
	v_lshlrev_b32_e32 v18, 16, v68
	v_and_b32_e32 v19, 0xffff0000, v68
	v_lshlrev_b32_e32 v20, 16, v69
	v_and_b32_e32 v21, 0xffff0000, v69
	v_pk_add_f32 v[14:15], v[14:15], v[20:21]
	v_pk_add_f32 v[12:13], v[12:13], v[18:19]
	v_lshlrev_b32_e32 v18, 16, v70
	v_and_b32_e32 v19, 0xffff0000, v70
	v_lshlrev_b32_e32 v20, 16, v71
	v_and_b32_e32 v21, 0xffff0000, v71
	v_pk_add_f32 v[20:21], v[10:11], v[20:21]
	v_pk_add_f32 v[10:11], v[8:9], v[18:19]
	v_mul_f32_e32 v8, v13, v13
	v_mul_f32_e32 v9, v15, v15
	v_fmac_f32_e32 v8, v12, v12
	v_fmac_f32_e32 v9, v14, v14
	v_add_f32_e32 v8, v8, v9
	v_mul_f32_e32 v9, v11, v11
	v_mul_f32_e32 v18, v21, v21
	v_fmac_f32_e32 v9, v10, v10
	v_fmac_f32_e32 v18, v20, v20
	v_add_f32_e32 v9, v9, v18
	v_add_f32_e32 v18, v8, v9
	v_cvt_pk_bf16_f32 v8, v12, v13
	v_cvt_pk_bf16_f32 v9, v14, v15
	s_nop 0
	v_lshlrev_b32_e32 v12, 16, v64
	v_and_b32_e32 v13, 0xffff0000, v64
	v_lshlrev_b32_e32 v14, 16, v65
	v_and_b32_e32 v15, 0xffff0000, v65
	v_pk_add_f32 v[6:7], v[6:7], v[14:15]
	v_pk_add_f32 v[4:5], v[4:5], v[12:13]
	v_lshlrev_b32_e32 v12, 16, v66
	v_and_b32_e32 v13, 0xffff0000, v66
	v_lshlrev_b32_e32 v14, 16, v67
	v_and_b32_e32 v15, 0xffff0000, v67
	v_pk_add_f32 v[12:13], v[0:1], v[12:13]
	v_mul_f32_e32 v0, v5, v5
	v_mul_f32_e32 v1, v7, v7
	v_pk_add_f32 v[14:15], v[2:3], v[14:15]
	v_fmac_f32_e32 v0, v4, v4
	v_fmac_f32_e32 v1, v6, v6
	v_add_f32_e32 v0, v0, v1
	v_mul_f32_e32 v1, v13, v13
	v_mul_f32_e32 v2, v15, v15
	v_fmac_f32_e32 v1, v12, v12
	v_fmac_f32_e32 v2, v14, v14
	v_add_f32_e32 v1, v1, v2
	v_add_f32_e32 v0, v0, v1
	v_add_f32_e32 v0, v18, v0
	ds_bpermute_b32 v1, v198, v0
	s_waitcnt lgkmcnt(1)
	v_lshl_add_u64 v[16:17], s[84:85], 0, v[92:93]
	v_lshl_add_u64 v[16:17], v[168:169], 1, v[16:17]
	v_cvt_pk_bf16_f32 v10, v10, v11
	v_cvt_pk_bf16_f32 v11, v20, v21
	s_waitcnt lgkmcnt(0)
	v_add_f32_e32 v0, v0, v1
	ds_bpermute_b32 v1, v197, v0
	v_cvt_pk_bf16_f32 v2, v4, v5
	v_cvt_pk_bf16_f32 v3, v6, v7
	v_cvt_pk_bf16_f32 v4, v12, v13
	v_cvt_pk_bf16_f32 v5, v14, v15
	global_store_dwordx4 v[16:17], v[8:11], off
	global_store_dwordx4 v[16:17], v[2:5], off offset:256
	s_and_saveexec_b64 s[6:7], s[38:39]
	s_cbranch_execz .LBB0_377
	s_waitcnt lgkmcnt(0)
	v_add_f32_e32 v0, v0, v1
	ds_write_b32 v190, v0 offset:704
.LBB0_377:
	s_or_b64 exec, exec, s[6:7]
	s_waitcnt lgkmcnt(0)
	s_barrier
	s_and_saveexec_b64 s[6:7], s[40:41]
	s_cbranch_execz .LBB0_379
	s_waitcnt lgkmcnt(0)
	ds_read2st64_b32 v[0:1], v195 offset1:4
	ds_read2st64_b32 v[2:3], v195 offset0:8 offset1:12
	s_ashr_i32 s13, s12, 31
	s_waitcnt lgkmcnt(1)
	v_mov_b32_e32 v4, v0
	s_waitcnt lgkmcnt(0)
	v_mov_b32_e32 v5, v2
	v_mov_b32_e32 v2, v1
	v_pk_add_f32 v[0:1], v[4:5], v[2:3]
	s_nop 0
	v_add_f32_e32 v2, v0, v1
	v_add_u32_e32 v0, s9, v176
	v_ashrrev_i32_e32 v1, 31, v0
	v_lshl_add_u64 v[0:1], v[0:1], 4, s[88:89]
	v_lshl_add_u64 v[0:1], s[12:13], 2, v[0:1]
	global_store_dword v[0:1], v2, off
